# P2 q/k-norm epilogue: rope cos/sin quads fetched one (ai,m) group ahead (sample tiles only), copied in at the old load site; per-group vmcnt(0) removed
# baseline (speedup 1.0000x reference)
.LBB0_374:
	v_add_u32_e32 v144, 0, v185
	v_add_u32_e32 v144, 0x20000, v144
	ds_read_b128 v[144:147], v144
	s_add_i32 s8, s70, -16
	s_lshl_b32 s2, s12, 1
	s_lshr_b32 s8, s8, 2
	s_add_i32 s2, s2, -16
	s_waitcnt lgkmcnt(0)
	v_mov_b32_e32 v174, v145
	v_mov_b32_e32 v175, v146
	v_mov_b32_e32 v145, v147
	v_pk_add_f32 v[144:145], v[174:175], v[144:145]
	s_mul_hi_u32 s9, s8, 0x600
	v_add_f32_e32 v144, v144, v145
	v_fmamk_f32 v144, v144, 0x3c000000, v209
	v_rsq_f32_e32 v144, v144
	s_mulk_i32 s8, 0x600
	s_add_u32 s74, s8, 0x200
	s_addc_u32 s75, s9, 0
	v_pk_mul_f32 v[120:121], v[120:121], v[144:145] op_sel_hi:[1,0]
	v_lshl_add_u64 v[146:147], s[74:75], 0, v[156:157]
	v_pk_mul_f32 v[126:127], v[126:127], v[144:145] op_sel_hi:[1,0]
	v_pk_mul_f32 v[124:125], v[124:125], v[144:145] op_sel_hi:[1,0]
	v_pk_mul_f32 v[122:123], v[122:123], v[144:145] op_sel_hi:[1,0]
	s_waitcnt vmcnt(0)
	s_cmp_eq_u64 s[10:11], 0
	s_cbranch_scc0 .Lrpf_1
	v_add_u32_e32 v222, s63, v186
	v_and_b32_e32 v222, 0x3df, v222
	v_lshrrev_b32_e32 v222, 6, v222
	v_cndmask_b32_e64 v222, v181, v222, s[6:7]
	v_lshlrev_b32_e32 v222, 7, v222
	v_mov_b32_e32 v223, v157
	v_lshl_add_u64 v[226:227], v[162:163], 0, v[222:223]
	v_lshl_add_u64 v[228:229], v[164:165], 0, v[222:223]
	global_load_dwordx4 v[214:217], v[226:227], off
	global_load_dwordx4 v[218:221], v[228:229], off
.Lrpf_1:
	v_pk_mul_f32 v[120:121], v[128:129], v[120:121]
	v_lshlrev_b64 v[174:175], 10, v[146:147]
	v_pk_mul_f32 v[146:147], v[132:133], v[124:125]
	v_pk_mul_f32 v[212:213], v[134:135], v[126:127]
	v_pk_mul_f32 v[122:123], v[130:131], v[122:123]
	v_pk_mul_f32 v[124:125], v[140:141], v[120:121]
	v_ashrrev_i32_e32 v179, 31, v178
	v_pk_mul_f32 v[126:127], v[142:143], v[122:123]
	v_pk_fma_f32 v[124:125], v[136:137], v[146:147], v[124:125] neg_lo:[0,0,1] neg_hi:[0,0,1]
	v_pk_mul_f32 v[144:145], v[140:141], v[146:147]
	v_pk_mul_f32 v[146:147], v[142:143], v[212:213]
	v_cndmask_b32_e64 v156, 0, 1, s[72:73]
	v_lshlrev_b64 v[176:177], 9, v[178:179]
	v_pk_fma_f32 v[126:127], v[138:139], v[212:213], v[126:127] neg_lo:[0,0,1] neg_hi:[0,0,1]
	v_pk_fma_f32 v[146:147], v[138:139], v[122:123], v[146:147]
	v_pk_fma_f32 v[144:145], v[136:137], v[120:121], v[144:145]
	s_mov_b64 s[80:81], -1
	s_and_b64 vcc, exec, s[78:79]
	v_cmp_ne_u32_e64 s[8:9], 1, v156
	v_cvt_pk_bf16_f32 v120, v124, v125
	v_cvt_pk_bf16_f32 v121, v126, v127
	v_cvt_pk_bf16_f32 v122, v144, v145
	v_cvt_pk_bf16_f32 v123, v146, v147
	s_cbranch_vccz .LBB0_380
	s_lshl_b32 s20, s2, 7
	v_or_b32_e32 v156, s20, v158
	s_mov_b64 s[70:71], -1
	s_and_b64 vcc, exec, s[8:9]
	v_lshlrev_b32_e32 v156, 1, v156
	s_cbranch_vccnz .LBB0_377
	v_lshl_add_u64 v[212:213], v[176:177], 1, s[52:53]
	v_lshl_add_u64 v[212:213], v[212:213], 0, v[156:157]
	global_store_dwordx4 v[212:213], v[120:123], off
	v_lshl_add_u64 v[212:213], v[176:177], 2, s[54:55]
	v_lshl_add_u64 v[212:213], s[20:21], 2, v[212:213]
	s_mov_b32 s77, s21
	v_lshl_add_u64 v[212:213], v[212:213], 0, s[76:77]
	v_mov_b32_e32 v173, v157
	v_lshl_add_u64 v[212:213], v[212:213], 0, v[172:173]
	s_mov_b64 s[70:71], 0
	global_store_dwordx4 v[212:213], v[124:127], off
	global_store_dwordx4 v[212:213], v[144:147], off offset:128

.LBB0_389:
	v_lshrrev_b32_e32 v112, 6, v156
	v_cndmask_b32_e64 v112, v181, v112, s[6:7]
	v_lshlrev_b32_e32 v112, 7, v112
	v_mov_b32_e32 v113, v157
	v_lshl_add_u64 v[114:115], v[162:163], 0, v[112:113]
	v_lshl_add_u64 v[116:117], v[164:165], 0, v[112:113]
	s_waitcnt vmcnt(2)
	v_mov_b32_e32 v112, v214
	v_mov_b32_e32 v113, v215
	v_mov_b32_e32 v114, v216
	v_mov_b32_e32 v115, v217
	v_mov_b32_e32 v116, v218
	v_mov_b32_e32 v117, v219
	v_mov_b32_e32 v118, v220
	v_mov_b32_e32 v119, v221
	s_branch .LBB0_393

.LBB0_393:
	v_add_u32_e32 v120, 0, v187
	v_add_u32_e32 v120, 0x20000, v120
	ds_read_b128 v[120:123], v120
	v_ashrrev_i32_e32 v139, 31, v138
	v_lshlrev_b64 v[136:137], 9, v[138:139]
	s_and_b64 vcc, exec, s[12:13]
	s_mov_b64 s[72:73], -1
	s_waitcnt lgkmcnt(0)
	v_mov_b32_e32 v126, v121
	v_mov_b32_e32 v127, v122
	v_mov_b32_e32 v121, v123
	v_pk_add_f32 v[120:121], v[126:127], v[120:121]
	v_lshl_add_u64 v[122:123], s[74:75], 0, v[156:157]
	v_add_f32_e32 v120, v120, v121
	v_fmamk_f32 v120, v120, 0x3c000000, v209
	v_rsq_f32_e32 v120, v120
	v_lshlrev_b64 v[126:127], 10, v[122:123]
	v_pk_mul_f32 v[104:105], v[104:105], v[120:121] op_sel_hi:[1,0]
	v_pk_mul_f32 v[110:111], v[110:111], v[120:121] op_sel_hi:[1,0]
	v_pk_mul_f32 v[108:109], v[108:109], v[120:121] op_sel_hi:[1,0]
	v_pk_mul_f32 v[106:107], v[106:107], v[120:121] op_sel_hi:[1,0]
	v_pk_mul_f32 v[104:105], v[128:129], v[104:105]
	v_pk_mul_f32 v[122:123], v[132:133], v[108:109]
	v_pk_mul_f32 v[140:141], v[134:135], v[110:111]
	v_pk_mul_f32 v[106:107], v[130:131], v[106:107]
	s_cmp_eq_u64 s[10:11], 0
	s_cbranch_scc0 .Lrpf_2
	v_add_u32_e32 v222, s63, v188
	v_and_b32_e32 v222, 0x3ef, v222
	v_lshrrev_b32_e32 v222, 6, v222
	v_cndmask_b32_e64 v222, v211, v222, s[6:7]
	v_lshlrev_b32_e32 v222, 7, v222
	v_mov_b32_e32 v223, v157
	v_lshl_add_u64 v[226:227], v[162:163], 0, v[222:223]
	v_lshl_add_u64 v[228:229], v[164:165], 0, v[222:223]
	global_load_dwordx4 v[214:217], v[226:227], off
	global_load_dwordx4 v[218:221], v[228:229], off
.Lrpf_2:
	v_pk_mul_f32 v[108:109], v[116:117], v[104:105]
	v_pk_mul_f32 v[110:111], v[118:119], v[106:107]
	v_pk_fma_f32 v[108:109], v[112:113], v[122:123], v[108:109] neg_lo:[0,0,1] neg_hi:[0,0,1]
	v_pk_mul_f32 v[120:121], v[116:117], v[122:123]
	v_pk_mul_f32 v[122:123], v[118:119], v[140:141]
	v_pk_fma_f32 v[110:111], v[114:115], v[140:141], v[110:111] neg_lo:[0,0,1] neg_hi:[0,0,1]
	v_pk_fma_f32 v[122:123], v[114:115], v[106:107], v[122:123]
	v_pk_fma_f32 v[120:121], v[112:113], v[104:105], v[120:121]
	v_cvt_pk_bf16_f32 v104, v108, v109
	v_cvt_pk_bf16_f32 v105, v110, v111
	s_nop 0
	v_cvt_pk_bf16_f32 v106, v120, v121
	v_cvt_pk_bf16_f32 v107, v122, v123
	s_cbranch_vccnz .LBB0_399
	s_lshl_b32 s20, s2, 7
	v_or_b32_e32 v125, s20, v158
	s_and_b64 vcc, exec, s[8:9]
	v_lshlrev_b32_e32 v156, 1, v125
	s_cbranch_vccnz .LBB0_396
	v_lshl_add_u64 v[140:141], v[136:137], 1, s[52:53]
	v_lshl_add_u64 v[140:141], v[140:141], 0, v[156:157]
	global_store_dwordx4 v[140:141], v[104:107], off
	v_lshl_add_u64 v[140:141], v[136:137], 2, s[54:55]
	v_lshl_add_u64 v[140:141], s[20:21], 2, v[140:141]
	s_mov_b32 s77, s21
	v_lshl_add_u64 v[140:141], v[140:141], 0, s[76:77]
	v_mov_b32_e32 v173, v157
	v_lshl_add_u64 v[140:141], v[140:141], 0, v[172:173]
	s_mov_b64 s[72:73], 0
	global_store_dwordx4 v[140:141], v[108:111], off
	global_store_dwordx4 v[140:141], v[120:123], off offset:128

.LBB0_408:
	v_lshrrev_b32_e32 v96, 6, v156
	v_cndmask_b32_e64 v96, v211, v96, s[6:7]
	v_lshlrev_b32_e32 v96, 7, v96
	v_mov_b32_e32 v97, v157
	v_lshl_add_u64 v[98:99], v[162:163], 0, v[96:97]
	v_lshl_add_u64 v[100:101], v[164:165], 0, v[96:97]
	s_waitcnt vmcnt(2)
	v_mov_b32_e32 v96, v214
	v_mov_b32_e32 v97, v215
	v_mov_b32_e32 v98, v216
	v_mov_b32_e32 v99, v217
	v_mov_b32_e32 v100, v218
	v_mov_b32_e32 v101, v219
	v_mov_b32_e32 v102, v220
	v_mov_b32_e32 v103, v221
	s_branch .LBB0_412

.LBB0_412:
	v_add_u32_e32 v104, 0, v189
	v_add_u32_e32 v104, 0x20000, v104
	ds_read_b128 v[104:107], v104
	v_ashrrev_i32_e32 v113, 31, v112
	v_lshlrev_b64 v[110:111], 9, v[112:113]
	s_and_b64 vcc, exec, s[12:13]
	s_mov_b64 s[72:73], -1
	s_waitcnt lgkmcnt(0)
	v_mov_b32_e32 v108, v105
	v_mov_b32_e32 v109, v106
	v_mov_b32_e32 v105, v107
	v_pk_add_f32 v[104:105], v[108:109], v[104:105]
	v_lshl_add_u64 v[106:107], s[74:75], 0, v[156:157]
	v_add_f32_e32 v104, v104, v105
	v_fmamk_f32 v104, v104, 0x3c000000, v209
	v_rsq_f32_e32 v104, v104
	v_lshlrev_b64 v[108:109], 10, v[106:107]
	v_pk_mul_f32 v[88:89], v[88:89], v[104:105] op_sel_hi:[1,0]
	v_pk_mul_f32 v[94:95], v[94:95], v[104:105] op_sel_hi:[1,0]
	v_pk_mul_f32 v[92:93], v[92:93], v[104:105] op_sel_hi:[1,0]
	v_pk_mul_f32 v[90:91], v[90:91], v[104:105] op_sel_hi:[1,0]
	v_pk_mul_f32 v[88:89], v[128:129], v[88:89]
	v_pk_mul_f32 v[106:107], v[132:133], v[92:93]
	v_pk_mul_f32 v[114:115], v[134:135], v[94:95]
	v_pk_mul_f32 v[90:91], v[130:131], v[90:91]
	s_cmp_eq_u64 s[10:11], 0
	s_cbranch_scc0 .Lrpf_3
	v_add_u32_e32 v222, s63, v190
	v_and_b32_e32 v222, 0x3ff, v222
	v_lshrrev_b32_e32 v222, 6, v222
	v_cndmask_b32_e64 v222, v254, v222, s[6:7]
	v_lshlrev_b32_e32 v222, 7, v222
	v_mov_b32_e32 v223, v157
	v_lshl_add_u64 v[226:227], v[162:163], 0, v[222:223]
	v_lshl_add_u64 v[228:229], v[164:165], 0, v[222:223]
	global_load_dwordx4 v[214:217], v[226:227], off
	global_load_dwordx4 v[218:221], v[228:229], off
.Lrpf_3:
	v_pk_mul_f32 v[92:93], v[100:101], v[88:89]
	v_pk_mul_f32 v[94:95], v[102:103], v[90:91]
	v_pk_fma_f32 v[92:93], v[96:97], v[106:107], v[92:93] neg_lo:[0,0,1] neg_hi:[0,0,1]
	v_pk_mul_f32 v[104:105], v[100:101], v[106:107]
	v_pk_mul_f32 v[106:107], v[102:103], v[114:115]
	v_pk_fma_f32 v[94:95], v[98:99], v[114:115], v[94:95] neg_lo:[0,0,1] neg_hi:[0,0,1]
	v_pk_fma_f32 v[106:107], v[98:99], v[90:91], v[106:107]
	v_pk_fma_f32 v[104:105], v[96:97], v[88:89], v[104:105]
	v_cvt_pk_bf16_f32 v88, v92, v93
	v_cvt_pk_bf16_f32 v89, v94, v95
	s_nop 0
	v_cvt_pk_bf16_f32 v90, v104, v105
	v_cvt_pk_bf16_f32 v91, v106, v107
	s_cbranch_vccnz .LBB0_418
	s_lshl_b32 s20, s2, 7
	v_or_b32_e32 v114, s20, v158
	s_and_b64 vcc, exec, s[8:9]
	v_lshlrev_b32_e32 v156, 1, v114
	s_cbranch_vccnz .LBB0_415
	v_lshl_add_u64 v[114:115], v[110:111], 1, s[52:53]
	v_lshl_add_u64 v[114:115], v[114:115], 0, v[156:157]
	global_store_dwordx4 v[114:115], v[88:91], off
	v_lshl_add_u64 v[114:115], v[110:111], 2, s[54:55]
	v_lshl_add_u64 v[114:115], s[20:21], 2, v[114:115]
	s_mov_b32 s77, s21
	v_lshl_add_u64 v[114:115], v[114:115], 0, s[76:77]
	v_mov_b32_e32 v173, v157
	v_lshl_add_u64 v[114:115], v[114:115], 0, v[172:173]
	s_mov_b64 s[72:73], 0
	global_store_dwordx4 v[114:115], v[92:95], off
	global_store_dwordx4 v[114:115], v[104:107], off offset:128

.LBB0_427:
	v_lshrrev_b32_e32 v80, 6, v156
	v_cndmask_b32_e64 v80, v254, v80, s[6:7]
	v_lshlrev_b32_e32 v80, 7, v80
	v_mov_b32_e32 v81, v157
	v_lshl_add_u64 v[82:83], v[162:163], 0, v[80:81]
	v_lshl_add_u64 v[84:85], v[164:165], 0, v[80:81]
	s_waitcnt vmcnt(2)
	v_mov_b32_e32 v80, v214
	v_mov_b32_e32 v81, v215
	v_mov_b32_e32 v82, v216
	v_mov_b32_e32 v83, v217
	v_mov_b32_e32 v84, v218
	v_mov_b32_e32 v85, v219
	v_mov_b32_e32 v86, v220
	v_mov_b32_e32 v87, v221
	s_branch .LBB0_431

.LBB0_431:
	v_add_u32_e32 v88, 0, v191
	v_add_u32_e32 v88, 0x20000, v88
	ds_read_b128 v[88:91], v88
	v_ashrrev_i32_e32 v97, 31, v96
	v_lshlrev_b64 v[94:95], 9, v[96:97]
	s_and_b64 vcc, exec, s[12:13]
	s_mov_b64 s[72:73], -1
	s_waitcnt lgkmcnt(0)
	v_mov_b32_e32 v92, v89
	v_mov_b32_e32 v93, v90
	v_mov_b32_e32 v89, v91
	v_pk_add_f32 v[88:89], v[92:93], v[88:89]
	v_lshl_add_u64 v[90:91], s[74:75], 0, v[156:157]
	v_add_f32_e32 v88, v88, v89
	v_fmamk_f32 v88, v88, 0x3c000000, v209
	v_rsq_f32_e32 v88, v88
	v_lshlrev_b64 v[92:93], 10, v[90:91]
	v_pk_mul_f32 v[72:73], v[72:73], v[88:89] op_sel_hi:[1,0]
	v_pk_mul_f32 v[78:79], v[78:79], v[88:89] op_sel_hi:[1,0]
	v_pk_mul_f32 v[76:77], v[76:77], v[88:89] op_sel_hi:[1,0]
	v_pk_mul_f32 v[74:75], v[74:75], v[88:89] op_sel_hi:[1,0]
	v_pk_mul_f32 v[72:73], v[128:129], v[72:73]
	v_pk_mul_f32 v[90:91], v[132:133], v[76:77]
	v_pk_mul_f32 v[98:99], v[134:135], v[78:79]
	v_pk_mul_f32 v[74:75], v[130:131], v[74:75]
	s_cmp_eq_u64 s[10:11], 0
	s_cbranch_scc0 .Lrpf_4
	v_add_u32_e32 v222, s63, v192
	v_and_b32_e32 v222, 0x3cf, v222
	v_lshrrev_b32_e32 v222, 6, v222
	v_cndmask_b32_e64 v222, v159, v222, s[6:7]
	v_lshlrev_b32_e32 v222, 7, v222
	v_mov_b32_e32 v223, v157
	v_lshl_add_u64 v[226:227], v[162:163], 0, v[222:223]
	v_lshl_add_u64 v[228:229], v[164:165], 0, v[222:223]
	global_load_dwordx4 v[214:217], v[226:227], off
	global_load_dwordx4 v[218:221], v[228:229], off
.Lrpf_4:
	v_pk_mul_f32 v[76:77], v[84:85], v[72:73]
	v_pk_mul_f32 v[78:79], v[86:87], v[74:75]
	v_pk_fma_f32 v[76:77], v[80:81], v[90:91], v[76:77] neg_lo:[0,0,1] neg_hi:[0,0,1]
	v_pk_mul_f32 v[88:89], v[84:85], v[90:91]
	v_pk_mul_f32 v[90:91], v[86:87], v[98:99]
	v_pk_fma_f32 v[78:79], v[82:83], v[98:99], v[78:79] neg_lo:[0,0,1] neg_hi:[0,0,1]
	v_pk_fma_f32 v[90:91], v[82:83], v[74:75], v[90:91]
	v_pk_fma_f32 v[88:89], v[80:81], v[72:73], v[88:89]
	v_cvt_pk_bf16_f32 v72, v76, v77
	v_cvt_pk_bf16_f32 v73, v78, v79
	s_nop 0
	v_cvt_pk_bf16_f32 v74, v88, v89
	v_cvt_pk_bf16_f32 v75, v90, v91
	s_cbranch_vccnz .LBB0_437
	s_lshl_b32 s20, s2, 7
	v_or_b32_e32 v98, s20, v158
	s_and_b64 vcc, exec, s[8:9]
	v_lshlrev_b32_e32 v156, 1, v98
	s_cbranch_vccnz .LBB0_434
	v_lshl_add_u64 v[98:99], v[94:95], 1, s[52:53]
	v_lshl_add_u64 v[98:99], v[98:99], 0, v[156:157]
	global_store_dwordx4 v[98:99], v[72:75], off
	v_lshl_add_u64 v[98:99], v[94:95], 2, s[54:55]
	v_lshl_add_u64 v[98:99], s[20:21], 2, v[98:99]
	s_mov_b32 s77, s21
	v_lshl_add_u64 v[98:99], v[98:99], 0, s[76:77]
	v_mov_b32_e32 v173, v157
	v_lshl_add_u64 v[98:99], v[98:99], 0, v[172:173]
	s_mov_b64 s[72:73], 0
	global_store_dwordx4 v[98:99], v[76:79], off
	global_store_dwordx4 v[98:99], v[88:91], off offset:128

.LBB0_446:
	v_lshrrev_b32_e32 v64, 6, v156
	v_cndmask_b32_e64 v64, v159, v64, s[6:7]
	v_lshlrev_b32_e32 v64, 7, v64
	v_mov_b32_e32 v65, v157
	v_lshl_add_u64 v[66:67], v[162:163], 0, v[64:65]
	v_lshl_add_u64 v[68:69], v[164:165], 0, v[64:65]
	s_waitcnt vmcnt(2)
	v_mov_b32_e32 v64, v214
	v_mov_b32_e32 v65, v215
	v_mov_b32_e32 v66, v216
	v_mov_b32_e32 v67, v217
	v_mov_b32_e32 v68, v218
	v_mov_b32_e32 v69, v219
	v_mov_b32_e32 v70, v220
	v_mov_b32_e32 v71, v221
	s_branch .LBB0_450

.LBB0_450:
	v_add_u32_e32 v72, 0, v193
	v_add_u32_e32 v72, 0x20000, v72
	ds_read_b128 v[72:75], v72
	v_ashrrev_i32_e32 v81, 31, v80
	v_lshlrev_b64 v[78:79], 9, v[80:81]
	s_and_b64 vcc, exec, s[12:13]
	s_mov_b64 s[72:73], -1
	s_waitcnt lgkmcnt(0)
	v_mov_b32_e32 v76, v73
	v_mov_b32_e32 v77, v74
	v_mov_b32_e32 v73, v75
	v_pk_add_f32 v[72:73], v[76:77], v[72:73]
	v_lshl_add_u64 v[74:75], s[74:75], 0, v[156:157]
	v_add_f32_e32 v72, v72, v73
	v_fmamk_f32 v72, v72, 0x3c000000, v209
	v_rsq_f32_e32 v72, v72
	v_lshlrev_b64 v[76:77], 10, v[74:75]
	v_pk_mul_f32 v[56:57], v[56:57], v[72:73] op_sel_hi:[1,0]
	v_pk_mul_f32 v[62:63], v[62:63], v[72:73] op_sel_hi:[1,0]
	v_pk_mul_f32 v[60:61], v[60:61], v[72:73] op_sel_hi:[1,0]
	v_pk_mul_f32 v[58:59], v[58:59], v[72:73] op_sel_hi:[1,0]
	v_pk_mul_f32 v[56:57], v[128:129], v[56:57]
	v_pk_mul_f32 v[74:75], v[132:133], v[60:61]
	v_pk_mul_f32 v[82:83], v[134:135], v[62:63]
	v_pk_mul_f32 v[58:59], v[130:131], v[58:59]
	s_cmp_eq_u64 s[10:11], 0
	s_cbranch_scc0 .Lrpf_5
	v_add_u32_e32 v222, s63, v194
	v_and_b32_e32 v222, 0x3df, v222
	v_lshrrev_b32_e32 v222, 6, v222
	v_cndmask_b32_e64 v222, v181, v222, s[6:7]
	v_lshlrev_b32_e32 v222, 7, v222
	v_mov_b32_e32 v223, v157
	v_lshl_add_u64 v[226:227], v[162:163], 0, v[222:223]
	v_lshl_add_u64 v[228:229], v[164:165], 0, v[222:223]
	global_load_dwordx4 v[214:217], v[226:227], off
	global_load_dwordx4 v[218:221], v[228:229], off
.Lrpf_5:
	v_pk_mul_f32 v[60:61], v[68:69], v[56:57]
	v_pk_mul_f32 v[62:63], v[70:71], v[58:59]
	v_pk_fma_f32 v[60:61], v[64:65], v[74:75], v[60:61] neg_lo:[0,0,1] neg_hi:[0,0,1]
	v_pk_mul_f32 v[72:73], v[68:69], v[74:75]
	v_pk_mul_f32 v[74:75], v[70:71], v[82:83]
	v_pk_fma_f32 v[62:63], v[66:67], v[82:83], v[62:63] neg_lo:[0,0,1] neg_hi:[0,0,1]
	v_pk_fma_f32 v[74:75], v[66:67], v[58:59], v[74:75]
	v_pk_fma_f32 v[72:73], v[64:65], v[56:57], v[72:73]
	v_cvt_pk_bf16_f32 v56, v60, v61
	v_cvt_pk_bf16_f32 v57, v62, v63
	s_nop 0
	v_cvt_pk_bf16_f32 v58, v72, v73
	v_cvt_pk_bf16_f32 v59, v74, v75
	s_cbranch_vccnz .LBB0_456
	s_lshl_b32 s20, s2, 7
	v_or_b32_e32 v82, s20, v158
	s_and_b64 vcc, exec, s[8:9]
	v_lshlrev_b32_e32 v156, 1, v82
	s_cbranch_vccnz .LBB0_453
	v_lshl_add_u64 v[82:83], v[78:79], 1, s[52:53]
	v_lshl_add_u64 v[82:83], v[82:83], 0, v[156:157]
	global_store_dwordx4 v[82:83], v[56:59], off
	v_lshl_add_u64 v[82:83], v[78:79], 2, s[54:55]
	v_lshl_add_u64 v[82:83], s[20:21], 2, v[82:83]
	s_mov_b32 s77, s21
	v_lshl_add_u64 v[82:83], v[82:83], 0, s[76:77]
	v_mov_b32_e32 v173, v157
	v_lshl_add_u64 v[82:83], v[82:83], 0, v[172:173]
	s_mov_b64 s[72:73], 0
	global_store_dwordx4 v[82:83], v[60:63], off
	global_store_dwordx4 v[82:83], v[72:75], off offset:128

.LBB0_465:
	v_lshrrev_b32_e32 v48, 6, v156
	v_cndmask_b32_e64 v48, v181, v48, s[6:7]
	v_lshlrev_b32_e32 v48, 7, v48
	v_mov_b32_e32 v49, v157
	v_lshl_add_u64 v[50:51], v[162:163], 0, v[48:49]
	v_lshl_add_u64 v[52:53], v[164:165], 0, v[48:49]
	s_waitcnt vmcnt(2)
	v_mov_b32_e32 v48, v214
	v_mov_b32_e32 v49, v215
	v_mov_b32_e32 v50, v216
	v_mov_b32_e32 v51, v217
	v_mov_b32_e32 v52, v218
	v_mov_b32_e32 v53, v219
	v_mov_b32_e32 v54, v220
	v_mov_b32_e32 v55, v221
	s_branch .LBB0_469

.LBB0_469:
	v_add_u32_e32 v56, 0, v195
	v_add_u32_e32 v56, 0x20000, v56
	ds_read_b128 v[56:59], v56
	v_ashrrev_i32_e32 v65, 31, v64
	v_lshlrev_b64 v[62:63], 9, v[64:65]
	s_and_b64 vcc, exec, s[12:13]
	s_mov_b64 s[72:73], -1
	s_waitcnt lgkmcnt(0)
	v_mov_b32_e32 v60, v57
	v_mov_b32_e32 v61, v58
	v_mov_b32_e32 v57, v59
	v_pk_add_f32 v[56:57], v[60:61], v[56:57]
	v_lshl_add_u64 v[58:59], s[74:75], 0, v[156:157]
	v_add_f32_e32 v56, v56, v57
	v_fmamk_f32 v56, v56, 0x3c000000, v209
	v_rsq_f32_e32 v56, v56
	v_lshlrev_b64 v[60:61], 10, v[58:59]
	v_pk_mul_f32 v[40:41], v[40:41], v[56:57] op_sel_hi:[1,0]
	v_pk_mul_f32 v[46:47], v[46:47], v[56:57] op_sel_hi:[1,0]
	v_pk_mul_f32 v[44:45], v[44:45], v[56:57] op_sel_hi:[1,0]
	v_pk_mul_f32 v[42:43], v[42:43], v[56:57] op_sel_hi:[1,0]
	v_pk_mul_f32 v[40:41], v[128:129], v[40:41]
	v_pk_mul_f32 v[58:59], v[132:133], v[44:45]
	v_pk_mul_f32 v[66:67], v[134:135], v[46:47]
	v_pk_mul_f32 v[42:43], v[130:131], v[42:43]
	s_cmp_eq_u64 s[10:11], 0
	s_cbranch_scc0 .Lrpf_6
	v_add_u32_e32 v222, s63, v196
	v_and_b32_e32 v222, 0x3ef, v222
	v_lshrrev_b32_e32 v222, 6, v222
	v_cndmask_b32_e64 v222, v211, v222, s[6:7]
	v_lshlrev_b32_e32 v222, 7, v222
	v_mov_b32_e32 v223, v157
	v_lshl_add_u64 v[226:227], v[162:163], 0, v[222:223]
	v_lshl_add_u64 v[228:229], v[164:165], 0, v[222:223]
	global_load_dwordx4 v[214:217], v[226:227], off
	global_load_dwordx4 v[218:221], v[228:229], off
.Lrpf_6:
	v_pk_mul_f32 v[44:45], v[52:53], v[40:41]
	v_pk_mul_f32 v[46:47], v[54:55], v[42:43]
	v_pk_fma_f32 v[44:45], v[48:49], v[58:59], v[44:45] neg_lo:[0,0,1] neg_hi:[0,0,1]
	v_pk_mul_f32 v[56:57], v[52:53], v[58:59]
	v_pk_mul_f32 v[58:59], v[54:55], v[66:67]
	v_pk_fma_f32 v[46:47], v[50:51], v[66:67], v[46:47] neg_lo:[0,0,1] neg_hi:[0,0,1]
	v_pk_fma_f32 v[58:59], v[50:51], v[42:43], v[58:59]
	v_pk_fma_f32 v[56:57], v[48:49], v[40:41], v[56:57]
	v_cvt_pk_bf16_f32 v40, v44, v45
	v_cvt_pk_bf16_f32 v41, v46, v47
	s_nop 0
	v_cvt_pk_bf16_f32 v42, v56, v57
	v_cvt_pk_bf16_f32 v43, v58, v59
	s_cbranch_vccnz .LBB0_475
	s_lshl_b32 s20, s2, 7
	v_or_b32_e32 v66, s20, v158
	s_and_b64 vcc, exec, s[8:9]
	v_lshlrev_b32_e32 v156, 1, v66
	s_cbranch_vccnz .LBB0_472
	v_lshl_add_u64 v[66:67], v[62:63], 1, s[52:53]
	v_lshl_add_u64 v[66:67], v[66:67], 0, v[156:157]
	global_store_dwordx4 v[66:67], v[40:43], off
	v_lshl_add_u64 v[66:67], v[62:63], 2, s[54:55]
	v_lshl_add_u64 v[66:67], s[20:21], 2, v[66:67]
	s_mov_b32 s77, s21
	v_lshl_add_u64 v[66:67], v[66:67], 0, s[76:77]
	v_mov_b32_e32 v173, v157
	v_lshl_add_u64 v[66:67], v[66:67], 0, v[172:173]
	s_mov_b64 s[72:73], 0
	global_store_dwordx4 v[66:67], v[44:47], off
	global_store_dwordx4 v[66:67], v[56:59], off offset:128

.LBB0_484:
	v_lshrrev_b32_e32 v32, 6, v156
	v_cndmask_b32_e64 v32, v211, v32, s[6:7]
	v_lshlrev_b32_e32 v32, 7, v32
	v_mov_b32_e32 v33, v157
	v_lshl_add_u64 v[34:35], v[162:163], 0, v[32:33]
	v_lshl_add_u64 v[36:37], v[164:165], 0, v[32:33]
	s_waitcnt vmcnt(2)
	v_mov_b32_e32 v32, v214
	v_mov_b32_e32 v33, v215
	v_mov_b32_e32 v34, v216
	v_mov_b32_e32 v35, v217
	v_mov_b32_e32 v36, v218
	v_mov_b32_e32 v37, v219
	v_mov_b32_e32 v38, v220
	v_mov_b32_e32 v39, v221
	s_branch .LBB0_488

.LBB0_488:
	v_add_u32_e32 v40, 0, v197
	v_add_u32_e32 v40, 0x20000, v40
	ds_read_b128 v[40:43], v40
	v_ashrrev_i32_e32 v49, 31, v48
	v_lshlrev_b64 v[46:47], 9, v[48:49]
	s_and_b64 vcc, exec, s[12:13]
	s_mov_b64 s[72:73], -1
	s_waitcnt lgkmcnt(0)
	v_mov_b32_e32 v44, v41
	v_mov_b32_e32 v45, v42
	v_mov_b32_e32 v41, v43
	v_pk_add_f32 v[40:41], v[44:45], v[40:41]
	v_lshl_add_u64 v[42:43], s[74:75], 0, v[156:157]
	v_add_f32_e32 v40, v40, v41
	v_fmamk_f32 v40, v40, 0x3c000000, v209
	v_rsq_f32_e32 v40, v40
	v_lshlrev_b64 v[44:45], 10, v[42:43]
	v_pk_mul_f32 v[24:25], v[24:25], v[40:41] op_sel_hi:[1,0]
	v_pk_mul_f32 v[30:31], v[30:31], v[40:41] op_sel_hi:[1,0]
	v_pk_mul_f32 v[28:29], v[28:29], v[40:41] op_sel_hi:[1,0]
	v_pk_mul_f32 v[26:27], v[26:27], v[40:41] op_sel_hi:[1,0]
	v_pk_mul_f32 v[24:25], v[128:129], v[24:25]
	v_pk_mul_f32 v[42:43], v[132:133], v[28:29]
	v_pk_mul_f32 v[50:51], v[134:135], v[30:31]
	v_pk_mul_f32 v[26:27], v[130:131], v[26:27]
	s_cmp_eq_u64 s[10:11], 0
	s_cbranch_scc0 .Lrpf_7
	v_add_u32_e32 v222, s63, v198
	v_and_b32_e32 v222, 0x3ff, v222
	v_lshrrev_b32_e32 v222, 6, v222
	v_cndmask_b32_e64 v222, v254, v222, s[6:7]
	v_lshlrev_b32_e32 v222, 7, v222
	v_mov_b32_e32 v223, v157
	v_lshl_add_u64 v[226:227], v[162:163], 0, v[222:223]
	v_lshl_add_u64 v[228:229], v[164:165], 0, v[222:223]
	global_load_dwordx4 v[214:217], v[226:227], off
	global_load_dwordx4 v[218:221], v[228:229], off
.Lrpf_7:
	v_pk_mul_f32 v[28:29], v[36:37], v[24:25]
	v_pk_mul_f32 v[30:31], v[38:39], v[26:27]
	v_pk_fma_f32 v[28:29], v[32:33], v[42:43], v[28:29] neg_lo:[0,0,1] neg_hi:[0,0,1]
	v_pk_mul_f32 v[40:41], v[36:37], v[42:43]
	v_pk_mul_f32 v[42:43], v[38:39], v[50:51]
	v_pk_fma_f32 v[30:31], v[34:35], v[50:51], v[30:31] neg_lo:[0,0,1] neg_hi:[0,0,1]
	v_pk_fma_f32 v[42:43], v[34:35], v[26:27], v[42:43]
	v_pk_fma_f32 v[40:41], v[32:33], v[24:25], v[40:41]
	v_cvt_pk_bf16_f32 v24, v28, v29
	v_cvt_pk_bf16_f32 v25, v30, v31
	s_nop 0
	v_cvt_pk_bf16_f32 v26, v40, v41
	v_cvt_pk_bf16_f32 v27, v42, v43
	s_cbranch_vccnz .LBB0_494
	s_lshl_b32 s20, s2, 7
	v_or_b32_e32 v50, s20, v158
	s_and_b64 vcc, exec, s[8:9]
	v_lshlrev_b32_e32 v156, 1, v50
	s_cbranch_vccnz .LBB0_491
	v_lshl_add_u64 v[50:51], v[46:47], 1, s[52:53]
	v_lshl_add_u64 v[50:51], v[50:51], 0, v[156:157]
	global_store_dwordx4 v[50:51], v[24:27], off
	v_lshl_add_u64 v[50:51], v[46:47], 2, s[54:55]
	v_lshl_add_u64 v[50:51], s[20:21], 2, v[50:51]
	s_mov_b32 s77, s21
	v_lshl_add_u64 v[50:51], v[50:51], 0, s[76:77]
	v_mov_b32_e32 v173, v157
	v_lshl_add_u64 v[50:51], v[50:51], 0, v[172:173]
	s_mov_b64 s[72:73], 0
	global_store_dwordx4 v[50:51], v[28:31], off
	global_store_dwordx4 v[50:51], v[40:43], off offset:128

.LBB0_503:
	v_lshrrev_b32_e32 v16, 6, v156
	v_cndmask_b32_e64 v16, v254, v16, s[6:7]
	v_lshlrev_b32_e32 v16, 7, v16
	v_mov_b32_e32 v17, v157
	v_lshl_add_u64 v[18:19], v[162:163], 0, v[16:17]
	v_lshl_add_u64 v[20:21], v[164:165], 0, v[16:17]
	s_waitcnt vmcnt(2)
	v_mov_b32_e32 v16, v214
	v_mov_b32_e32 v17, v215
	v_mov_b32_e32 v18, v216
	v_mov_b32_e32 v19, v217
	v_mov_b32_e32 v20, v218
	v_mov_b32_e32 v21, v219
	v_mov_b32_e32 v22, v220
	v_mov_b32_e32 v23, v221
	s_branch .LBB0_507

.LBB0_507:
	v_add_u32_e32 v24, 0, v199
	v_add_u32_e32 v24, 0x20000, v24
	ds_read_b128 v[24:27], v24
	v_ashrrev_i32_e32 v33, 31, v32
	v_lshlrev_b64 v[30:31], 9, v[32:33]
	s_and_b64 vcc, exec, s[12:13]
	s_mov_b64 s[10:11], -1
	s_waitcnt lgkmcnt(0)
	v_mov_b32_e32 v28, v25
	v_mov_b32_e32 v29, v26
	v_mov_b32_e32 v25, v27
	v_pk_add_f32 v[24:25], v[28:29], v[24:25]
	v_lshl_add_u64 v[26:27], s[74:75], 0, v[156:157]
	v_add_f32_e32 v24, v24, v25
	v_fmamk_f32 v24, v24, 0x3c000000, v209
	v_rsq_f32_e32 v24, v24
	v_lshlrev_b64 v[28:29], 10, v[26:27]
	v_pk_mul_f32 v[8:9], v[8:9], v[24:25] op_sel_hi:[1,0]
	v_pk_mul_f32 v[14:15], v[14:15], v[24:25] op_sel_hi:[1,0]
	v_pk_mul_f32 v[12:13], v[12:13], v[24:25] op_sel_hi:[1,0]
	v_pk_mul_f32 v[10:11], v[10:11], v[24:25] op_sel_hi:[1,0]
	v_pk_mul_f32 v[8:9], v[128:129], v[8:9]
	v_pk_mul_f32 v[26:27], v[132:133], v[12:13]
	v_pk_mul_f32 v[34:35], v[134:135], v[14:15]
	v_pk_mul_f32 v[10:11], v[130:131], v[10:11]
	v_pk_mul_f32 v[12:13], v[20:21], v[8:9]
	v_pk_mul_f32 v[14:15], v[22:23], v[10:11]
	v_pk_fma_f32 v[12:13], v[16:17], v[26:27], v[12:13] neg_lo:[0,0,1] neg_hi:[0,0,1]
	v_pk_mul_f32 v[24:25], v[20:21], v[26:27]
	v_pk_mul_f32 v[26:27], v[22:23], v[34:35]
	v_pk_fma_f32 v[14:15], v[18:19], v[34:35], v[14:15] neg_lo:[0,0,1] neg_hi:[0,0,1]
	v_pk_fma_f32 v[26:27], v[18:19], v[10:11], v[26:27]
	v_pk_fma_f32 v[24:25], v[16:17], v[8:9], v[24:25]
	v_cvt_pk_bf16_f32 v8, v12, v13
	v_cvt_pk_bf16_f32 v9, v14, v15
	s_nop 0
	v_cvt_pk_bf16_f32 v10, v24, v25
	v_cvt_pk_bf16_f32 v11, v26, v27
	s_cbranch_vccnz .LBB0_513
	s_lshl_b32 s20, s2, 7
	v_or_b32_e32 v34, s20, v158
	s_and_b64 vcc, exec, s[8:9]
	v_lshlrev_b32_e32 v156, 1, v34
	s_cbranch_vccnz .LBB0_510
	v_lshl_add_u64 v[34:35], v[30:31], 1, s[52:53]
	v_lshl_add_u64 v[34:35], v[34:35], 0, v[156:157]
	global_store_dwordx4 v[34:35], v[8:11], off
	v_lshl_add_u64 v[34:35], v[30:31], 2, s[54:55]
	v_lshl_add_u64 v[34:35], s[20:21], 2, v[34:35]
	s_mov_b32 s77, s21
	v_lshl_add_u64 v[34:35], v[34:35], 0, s[76:77]
	v_mov_b32_e32 v173, v157
	v_lshl_add_u64 v[34:35], v[34:35], 0, v[172:173]
	s_mov_b64 s[10:11], 0
	global_store_dwordx4 v[34:35], v[12:15], off
	global_store_dwordx4 v[34:35], v[24:27], off offset:128
